# previous best plus 64 v_mov_b64 instead of 128 v_mov_b32 for the FFN-in accumulator clear between tiles
# speedup vs baseline: 1.0119x; 1.0119x over previous
.LBB0_344:
	s_ashr_i32 s19, s18, 31
	s_lshl_b64 s[20:21], s[18:19], 19
	s_add_u32 s15, s27, s20
	s_addc_u32 s19, s30, s21
	s_ashr_i32 s17, s16, 31
	s_lshl_b64 s[22:23], s[16:17], 11
	s_add_u32 s20, s15, s22
	s_addc_u32 s21, s19, s23
	s_and_b64 s[50:51], s[0:1], exec
	s_cselect_b32 s17, s21, s55
	s_cselect_b32 s19, s20, s54
	s_ashr_i32 s15, s14, 31
	s_lshl_b64 s[50:51], s[14:15], 19
	s_add_u32 s15, s31, s50
	s_addc_u32 s50, s33, s51
	s_add_u32 s22, s15, s22
	s_addc_u32 s23, s50, s23
	s_and_b64 s[50:51], s[0:1], exec
	s_cselect_b32 s15, s23, s43
	s_cselect_b32 s50, s22, s42
	s_add_u32 s56, s54, 0x40080
	s_addc_u32 s57, s55, 0
	s_add_u32 s51, s42, 0x100
	v_mov_b64_e32 v[0:1], 0
	v_mov_b64_e32 v[2:3], 0
	v_mov_b64_e32 v[4:5], 0
	v_mov_b64_e32 v[6:7], 0
	v_mov_b64_e32 v[8:9], 0
	v_mov_b64_e32 v[10:11], 0
	v_mov_b64_e32 v[12:13], 0
	v_mov_b64_e32 v[14:15], 0
	v_mov_b64_e32 v[16:17], 0
	v_mov_b64_e32 v[18:19], 0
	v_mov_b64_e32 v[20:21], 0
	v_mov_b64_e32 v[22:23], 0
	v_mov_b64_e32 v[24:25], 0
	v_mov_b64_e32 v[26:27], 0
	v_mov_b64_e32 v[28:29], 0
	v_mov_b64_e32 v[30:31], 0
	v_mov_b64_e32 v[32:33], 0
	v_mov_b64_e32 v[34:35], 0
	v_mov_b64_e32 v[36:37], 0
	v_mov_b64_e32 v[38:39], 0
	v_mov_b64_e32 v[40:41], 0
	v_mov_b64_e32 v[42:43], 0
	v_mov_b64_e32 v[44:45], 0
	v_mov_b64_e32 v[46:47], 0
	v_mov_b64_e32 v[48:49], 0
	v_mov_b64_e32 v[50:51], 0
	v_mov_b64_e32 v[52:53], 0
	v_mov_b64_e32 v[54:55], 0
	v_mov_b64_e32 v[56:57], 0
	v_mov_b64_e32 v[58:59], 0
	v_mov_b64_e32 v[60:61], 0
	v_mov_b64_e32 v[62:63], 0
	v_mov_b64_e32 v[64:65], 0
	v_mov_b64_e32 v[66:67], 0
	v_mov_b64_e32 v[68:69], 0
	v_mov_b64_e32 v[70:71], 0
	v_mov_b64_e32 v[72:73], 0
	v_mov_b64_e32 v[74:75], 0
	v_mov_b64_e32 v[76:77], 0
	v_mov_b64_e32 v[78:79], 0
	v_mov_b64_e32 v[80:81], 0
	v_mov_b64_e32 v[82:83], 0
	v_mov_b64_e32 v[84:85], 0
	v_mov_b64_e32 v[86:87], 0
	v_mov_b64_e32 v[88:89], 0
	v_mov_b64_e32 v[90:91], 0
	v_mov_b64_e32 v[92:93], 0
	v_mov_b64_e32 v[94:95], 0
	v_mov_b64_e32 v[96:97], 0
	v_mov_b64_e32 v[98:99], 0
	v_mov_b64_e32 v[100:101], 0
	v_mov_b64_e32 v[102:103], 0
	v_mov_b64_e32 v[104:105], 0
	v_mov_b64_e32 v[106:107], 0
	v_mov_b64_e32 v[108:109], 0
	v_mov_b64_e32 v[110:111], 0
	v_mov_b64_e32 v[112:113], 0
	v_mov_b64_e32 v[114:115], 0
	v_mov_b64_e32 v[116:117], 0
	v_mov_b64_e32 v[118:119], 0
	v_mov_b64_e32 v[120:121], 0
	v_mov_b64_e32 v[122:123], 0
	v_mov_b64_e32 v[124:125], 0
	v_mov_b64_e32 v[126:127], 0
	s_addc_u32 s53, s43, 0
	s_mov_b32 s58, -2
